# prep: ada k-loop unrolled x2 with the next step's 4 weight rows in flight; transpose split 17 / 29 tiles
# speedup vs baseline: 1.0022x; 1.0022x over previous
.LBB0_5:
	s_or_b64 exec, exec, s[6:7]
	s_mov_b64 s[26:27], s[94:95]
	s_load_dwordx4 s[8:11], s[26:27], 0x10
	s_load_dwordx4 s[12:15], s[26:27], 0x50
	s_load_dwordx2 s[22:23], s[26:27], 0x60
	s_load_dwordx2 s[6:7], s[26:27], 0xd0
	v_mov_b32_e32 v6, v214
	s_cmpk_gt_i32 s2, 0x13ff
	s_cbranch_scc1 .LBB0_19
	s_waitcnt lgkmcnt(0)
	s_add_u32 s0, s6, 0x2400000
	s_load_dwordx4 s[16:19], s[26:27], 0x88
	s_load_dwordx2 s[24:25], s[26:27], 0xc0
	s_addc_u32 s1, s7, 0
	s_add_u32 s3, s6, 0x1400000
	s_addc_u32 s4, s7, 0
	s_add_u32 s5, s6, 0x1000000
	s_addc_u32 s33, s7, 0
	s_mov_b32 s27, 0
	v_mov_b32_e32 v3, 0
	s_movk_i32 s44, 0x104
	s_mov_b32 s45, s2
	s_mov_b32 s48, s42
	s_movk_i32 s49, 0x1400
	s_cmpk_lg_i32 s42, 0x100
	s_cbranch_scc1 .Lprep_split_done
	s_add_i32 s45, s2, 0xcc0
	s_sub_i32 s50, s2, 64
	s_cmp_lt_u32 s2, 64
	s_cselect_b32 s48, 64, 0xc0
	s_movk_i32 s51, 0xcc0
	s_cselect_b32 s49, s49, s51
	s_cselect_b32 s45, s45, s50

.LBB0_30:
	s_or_b64 exec, exec, s[16:17]
	s_mul_hi_i32 s6, s0, 0x2aaaaaab
	s_lshr_b32 s7, s6, 31
	s_ashr_i32 s6, s6, 3
	s_add_i32 s22, s6, s7
	s_mul_i32 s6, s22, 48
	s_sub_i32 s6, s0, s6
	s_lshl_b32 s16, s6, 6
	s_ashr_i32 s17, s16, 31
	s_mul_i32 s19, s22, 0xc00000
	s_lshl_b64 s[6:7], s[16:17], 2
	s_mul_hi_i32 s18, s22, 0xc00000
	s_add_u32 s6, s19, s6
	s_addc_u32 s7, s18, s7
	v_mov_b32_e32 v16, 0
	v_lshl_add_u64 v[18:19], v[14:15], 0, s[6:7]
	s_mov_b64 s[18:19], 0
	v_mov_b32_e32 v8, v41
	v_mov_b32_e32 v43, v40
	v_mov_b32_e32 v17, v16
	v_mov_b32_e32 v20, v16
	v_mov_b32_e32 v21, v16
	v_mov_b32_e32 v22, v16
	v_mov_b32_e32 v23, v16
	v_mov_b32_e32 v24, v16
	v_mov_b32_e32 v25, v16
	v_mov_b32_e32 v26, v16
	v_mov_b32_e32 v27, v16
	v_mov_b32_e32 v28, v16
	v_mov_b32_e32 v29, v16
	v_mov_b32_e32 v30, v16
	v_mov_b32_e32 v31, v16
	v_mov_b32_e32 v32, v16
	v_mov_b32_e32 v33, v16
	v_mov_b32_e32 v34, v16
	v_mov_b32_e32 v35, v16
	v_mov_b32_e32 v36, v16
	v_mov_b32_e32 v37, v16
	s_waitcnt lgkmcnt(0)
	s_barrier
	v_add_co_u32_e64 v142, s[6:7], s5, v18
	s_nop 0
	v_addc_co_u32_e64 v143, s[6:7], -1, v19, s[6:7]
	v_add_co_u32_e64 v144, s[6:7], s24, v18
	s_nop 0
	v_addc_co_u32_e64 v145, s[6:7], -1, v19, s[6:7]
	v_add_co_u32_e64 v146, s[6:7], s25, v18
	s_nop 0
	v_addc_co_u32_e64 v147, s[6:7], -1, v19, s[6:7]
	global_load_dword v120, v[18:19], off
	global_load_dword v122, v[144:145], off
	global_load_dword v124, v[146:147], off
	global_load_dword v126, v[142:143], off
.LBB0_31:
	v_add_u32_e32 v148, 4, v43
	v_mov_b32_e32 v149, s12
	v_cmp_lt_i32_e64 s[6:7], v148, v39
	s_nop 1
	v_cndmask_b32_e64 v148, 0, v149, s[6:7]
	v_mov_b32_e32 v149, 0
	v_lshl_add_u64 v[140:141], v[18:19], 0, v[148:149]
	v_add_co_u32_e64 v142, s[6:7], s5, v140
	s_nop 0
	v_addc_co_u32_e64 v143, s[6:7], -1, v141, s[6:7]
	v_add_co_u32_e64 v144, s[6:7], s24, v140
	s_nop 0
	v_addc_co_u32_e64 v145, s[6:7], -1, v141, s[6:7]
	v_add_co_u32_e64 v146, s[6:7], s25, v140
	s_nop 0
	v_addc_co_u32_e64 v147, s[6:7], -1, v141, s[6:7]
	global_load_dword v132, v[140:141], off
	global_load_dword v134, v[144:145], off
	global_load_dword v136, v[146:147], off
	global_load_dword v138, v[142:143], off
	v_add_u32_e32 v58, 0xffff0000, v8
	v_add_u32_e32 v60, 0xffff1000, v8
	ds_read_b128 v[44:47], v8
	ds_read_b128 v[2:5], v8 offset:4096
	ds_read_b128 v[48:51], v8 offset:8192
	ds_read_b128 v[52:55], v8 offset:12288
	ds_read_b128 v[56:59], v58
	ds_read_b128 v[60:63], v60
	v_add_u32_e32 v68, 0xffff2000, v8
	v_add_u32_e32 v69, 0xffff3000, v8
	v_add_u32_e32 v72, 0xffff4000, v8
	v_add_u32_e32 v76, 0xffff5000, v8
	v_add_u32_e32 v80, 0xffff6000, v8
	v_add_u32_e32 v84, 0xffff7000, v8
	v_add_u32_e32 v88, 0xffff8000, v8
	v_add_u32_e32 v92, 0xffff9000, v8
	v_add_u32_e32 v96, 0xffffa000, v8
	v_add_u32_e32 v100, 0xffffb000, v8
	v_add_u32_e32 v104, 0xffffc000, v8
	v_add_u32_e32 v108, 0xffffd000, v8
	v_add_u32_e32 v112, 0xffffe000, v8
	v_add_u32_e32 v116, 0xfffff000, v8
	ds_read_b128 v[64:67], v68
	ds_read_b128 v[68:71], v69
	ds_read_b128 v[72:75], v72
	ds_read_b128 v[76:79], v76
	ds_read_b128 v[80:83], v80
	ds_read_b128 v[84:87], v84
	ds_read_b128 v[88:91], v88
	ds_read_b128 v[92:95], v92
	ds_read_b128 v[96:99], v96
	ds_read_b128 v[100:103], v100
	ds_read_b128 v[104:107], v104
	ds_read_b128 v[108:111], v108
	ds_read_b128 v[112:115], v112
	ds_read_b128 v[116:119], v116
	s_waitcnt lgkmcnt(14)
	v_mov_b32_e32 v129, v2
	v_mov_b32_e32 v2, v45
	v_mov_b32_e32 v45, v4
	v_mov_b32_e32 v4, v47
	v_mov_b32_e32 v47, v60
	v_mov_b32_e32 v60, v57
	v_mov_b32_e32 v57, v62
	v_mov_b32_e32 v62, v59
	s_waitcnt lgkmcnt(12)
	v_mov_b32_e32 v59, v68
	v_mov_b32_e32 v68, v65
	v_mov_b32_e32 v65, v70
	v_mov_b32_e32 v70, v67
	s_waitcnt lgkmcnt(10)
	v_mov_b32_e32 v67, v76
	v_mov_b32_e32 v76, v73
	v_mov_b32_e32 v73, v78
	v_mov_b32_e32 v78, v75
	s_waitcnt lgkmcnt(8)
	v_mov_b32_e32 v75, v84
	v_mov_b32_e32 v84, v81
	v_mov_b32_e32 v81, v86
	v_mov_b32_e32 v86, v83
	s_waitcnt lgkmcnt(6)
	v_mov_b32_e32 v83, v92
	v_mov_b32_e32 v92, v89
	v_mov_b32_e32 v89, v94
	v_mov_b32_e32 v94, v91
	s_waitcnt lgkmcnt(4)
	v_mov_b32_e32 v91, v100
	v_mov_b32_e32 v100, v97
	v_mov_b32_e32 v97, v102
	v_mov_b32_e32 v102, v99
	s_waitcnt lgkmcnt(2)
	v_mov_b32_e32 v99, v108
	v_mov_b32_e32 v108, v105
	v_mov_b32_e32 v105, v110
	v_mov_b32_e32 v110, v107
	s_waitcnt lgkmcnt(0)
	v_mov_b32_e32 v107, v116
	v_mov_b32_e32 v116, v113
	v_mov_b32_e32 v128, v44
	v_mov_b32_e32 v44, v46
	v_mov_b32_e32 v46, v56
	v_mov_b32_e32 v56, v58
	v_mov_b32_e32 v58, v64
	v_mov_b32_e32 v64, v66
	v_mov_b32_e32 v66, v72
	v_mov_b32_e32 v72, v74
	v_mov_b32_e32 v74, v80
	v_mov_b32_e32 v80, v82
	v_mov_b32_e32 v82, v88
	v_mov_b32_e32 v88, v90
	v_mov_b32_e32 v90, v96
	v_mov_b32_e32 v96, v98
	v_mov_b32_e32 v98, v104
	v_mov_b32_e32 v104, v106
	v_mov_b32_e32 v106, v112
	v_mov_b32_e32 v112, v114
	v_mov_b32_e32 v113, v118
	v_add_u32_e32 v43, 4, v43
	v_mov_b32_e32 v118, v115
	v_cmp_ge_i32_e64 s[6:7], v43, v39
	v_add_u32_e32 v8, 16, v8
	v_lshl_add_u64 v[18:19], v[18:19], 0, s[12:13]
	s_or_b64 s[18:19], s[6:7], s[18:19]
	s_waitcnt vmcnt(4)
	v_mul_f32_e32 v114, v120, v51
	v_pk_mul_f32 v[60:61], v[122:123], v[60:61] op_sel_hi:[0,1]
	v_pk_mul_f32 v[68:69], v[122:123], v[68:69] op_sel_hi:[0,1]
	v_pk_mul_f32 v[76:77], v[122:123], v[76:77] op_sel_hi:[0,1]
	v_pk_mul_f32 v[84:85], v[122:123], v[84:85] op_sel_hi:[0,1]
	v_pk_mul_f32 v[92:93], v[122:123], v[92:93] op_sel_hi:[0,1]
	v_pk_mul_f32 v[100:101], v[122:123], v[100:101] op_sel_hi:[0,1]
	v_pk_mul_f32 v[108:109], v[122:123], v[108:109] op_sel_hi:[0,1]
	v_pk_mul_f32 v[116:117], v[122:123], v[116:117] op_sel_hi:[0,1]
	v_pk_mul_f32 v[2:3], v[122:123], v[2:3] op_sel_hi:[0,1]
	v_pk_fma_f32 v[46:47], v[126:127], v[46:47], v[60:61] op_sel_hi:[0,1,1]
	v_pk_fma_f32 v[58:59], v[126:127], v[58:59], v[68:69] op_sel_hi:[0,1,1]
	v_pk_fma_f32 v[60:61], v[126:127], v[66:67], v[76:77] op_sel_hi:[0,1,1]
	v_pk_fma_f32 v[66:67], v[126:127], v[74:75], v[84:85] op_sel_hi:[0,1,1]
	v_pk_fma_f32 v[68:69], v[126:127], v[82:83], v[92:93] op_sel_hi:[0,1,1]
	v_pk_fma_f32 v[74:75], v[126:127], v[90:91], v[100:101] op_sel_hi:[0,1,1]
	v_pk_fma_f32 v[76:77], v[126:127], v[98:99], v[108:109] op_sel_hi:[0,1,1]
	v_pk_fma_f32 v[82:83], v[126:127], v[106:107], v[116:117] op_sel_hi:[0,1,1]
	v_pk_fma_f32 v[2:3], v[126:127], v[128:129], v[2:3] op_sel_hi:[0,1,1]
	v_mov_b32_e32 v127, v122
	v_pk_fma_f32 v[46:47], v[124:125], v[56:57], v[46:47] op_sel_hi:[0,1,1]
	v_pk_fma_f32 v[56:57], v[124:125], v[64:65], v[58:59] op_sel_hi:[0,1,1]
	v_pk_fma_f32 v[58:59], v[124:125], v[72:73], v[60:61] op_sel_hi:[0,1,1]
	v_pk_fma_f32 v[60:61], v[124:125], v[80:81], v[66:67] op_sel_hi:[0,1,1]
	v_pk_fma_f32 v[64:65], v[124:125], v[88:89], v[68:69] op_sel_hi:[0,1,1]
	v_pk_fma_f32 v[66:67], v[124:125], v[96:97], v[74:75] op_sel_hi:[0,1,1]
	v_pk_fma_f32 v[68:69], v[124:125], v[104:105], v[76:77] op_sel_hi:[0,1,1]
	v_pk_fma_f32 v[72:73], v[124:125], v[112:113], v[82:83] op_sel_hi:[0,1,1]
	v_pk_fma_f32 v[2:3], v[124:125], v[44:45], v[2:3] op_sel_hi:[0,1,1]
	v_mov_b32_e32 v125, v120
	v_pk_mul_f32 v[44:45], v[126:127], v[52:53]
	v_mul_f32_e32 v48, v126, v48
	v_mul_f32_e32 v130, v122, v49
	v_pk_fma_f32 v[2:3], v[120:121], v[4:5], v[2:3] op_sel_hi:[0,1,1]
	v_pk_mul_f32 v[4:5], v[124:125], v[54:55]
	v_mov_b32_e32 v49, v44
	v_mov_b32_e32 v131, v45
	v_mul_f32_e32 v50, v124, v50
	v_pk_add_f32 v[36:37], v[36:37], v[2:3]
	v_pk_add_f32 v[2:3], v[48:49], v[130:131]
	v_mov_b32_e32 v51, v4
	v_mov_b32_e32 v115, v5
	v_pk_add_f32 v[2:3], v[50:51], v[2:3]
	v_pk_fma_f32 v[46:47], v[120:121], v[62:63], v[46:47] op_sel_hi:[0,1,1]
	v_pk_fma_f32 v[52:53], v[120:121], v[70:71], v[56:57] op_sel_hi:[0,1,1]
	v_pk_fma_f32 v[56:57], v[120:121], v[78:79], v[58:59] op_sel_hi:[0,1,1]
	v_pk_fma_f32 v[58:59], v[120:121], v[86:87], v[60:61] op_sel_hi:[0,1,1]
	v_pk_fma_f32 v[60:61], v[120:121], v[94:95], v[64:65] op_sel_hi:[0,1,1]
	v_pk_fma_f32 v[62:63], v[120:121], v[102:103], v[66:67] op_sel_hi:[0,1,1]
	v_pk_fma_f32 v[64:65], v[120:121], v[110:111], v[68:69] op_sel_hi:[0,1,1]
	v_pk_fma_f32 v[66:67], v[120:121], v[118:119], v[72:73] op_sel_hi:[0,1,1]
	v_pk_add_f32 v[2:3], v[114:115], v[2:3]
	v_pk_add_f32 v[20:21], v[20:21], v[46:47]
	v_pk_add_f32 v[22:23], v[22:23], v[52:53]
	v_pk_add_f32 v[24:25], v[24:25], v[56:57]
	v_pk_add_f32 v[26:27], v[26:27], v[58:59]
	v_pk_add_f32 v[28:29], v[28:29], v[60:61]
	v_pk_add_f32 v[30:31], v[30:31], v[62:63]
	v_pk_add_f32 v[32:33], v[32:33], v[64:65]
	v_pk_add_f32 v[34:35], v[34:35], v[66:67]
	v_pk_add_f32 v[16:17], v[16:17], v[2:3]
	s_andn2_b64 exec, exec, s[18:19]
	s_cbranch_execz .Lada_kdone
	v_add_u32_e32 v148, 4, v43
	v_mov_b32_e32 v149, s12
	v_cmp_lt_i32_e64 s[6:7], v148, v39
	s_nop 1
	v_cndmask_b32_e64 v148, 0, v149, s[6:7]
	v_mov_b32_e32 v149, 0
	v_lshl_add_u64 v[140:141], v[18:19], 0, v[148:149]
	v_add_co_u32_e64 v142, s[6:7], s5, v140
	s_nop 0
	v_addc_co_u32_e64 v143, s[6:7], -1, v141, s[6:7]
	v_add_co_u32_e64 v144, s[6:7], s24, v140
	s_nop 0
	v_addc_co_u32_e64 v145, s[6:7], -1, v141, s[6:7]
	v_add_co_u32_e64 v146, s[6:7], s25, v140
	s_nop 0
	v_addc_co_u32_e64 v147, s[6:7], -1, v141, s[6:7]
	global_load_dword v120, v[140:141], off
	global_load_dword v122, v[144:145], off
	global_load_dword v124, v[146:147], off
	global_load_dword v126, v[142:143], off
	v_add_u32_e32 v58, 0xffff0000, v8
	v_add_u32_e32 v60, 0xffff1000, v8
	ds_read_b128 v[44:47], v8
	ds_read_b128 v[2:5], v8 offset:4096
	ds_read_b128 v[48:51], v8 offset:8192
	ds_read_b128 v[52:55], v8 offset:12288
	ds_read_b128 v[56:59], v58
	ds_read_b128 v[60:63], v60
	v_add_u32_e32 v68, 0xffff2000, v8
	v_add_u32_e32 v69, 0xffff3000, v8
	v_add_u32_e32 v72, 0xffff4000, v8
	v_add_u32_e32 v76, 0xffff5000, v8
	v_add_u32_e32 v80, 0xffff6000, v8
	v_add_u32_e32 v84, 0xffff7000, v8
	v_add_u32_e32 v88, 0xffff8000, v8
	v_add_u32_e32 v92, 0xffff9000, v8
	v_add_u32_e32 v96, 0xffffa000, v8
	v_add_u32_e32 v100, 0xffffb000, v8
	v_add_u32_e32 v104, 0xffffc000, v8
	v_add_u32_e32 v108, 0xffffd000, v8
	v_add_u32_e32 v112, 0xffffe000, v8
	v_add_u32_e32 v116, 0xfffff000, v8
	ds_read_b128 v[64:67], v68
	ds_read_b128 v[68:71], v69
	ds_read_b128 v[72:75], v72
	ds_read_b128 v[76:79], v76
	ds_read_b128 v[80:83], v80
	ds_read_b128 v[84:87], v84
	ds_read_b128 v[88:91], v88
	ds_read_b128 v[92:95], v92
	ds_read_b128 v[96:99], v96
	ds_read_b128 v[100:103], v100
	ds_read_b128 v[104:107], v104
	ds_read_b128 v[108:111], v108
	ds_read_b128 v[112:115], v112
	ds_read_b128 v[116:119], v116
	s_waitcnt lgkmcnt(14)
	v_mov_b32_e32 v129, v2
	v_mov_b32_e32 v2, v45
	v_mov_b32_e32 v45, v4
	v_mov_b32_e32 v4, v47
	v_mov_b32_e32 v47, v60
	v_mov_b32_e32 v60, v57
	v_mov_b32_e32 v57, v62
	v_mov_b32_e32 v62, v59
	s_waitcnt lgkmcnt(12)
	v_mov_b32_e32 v59, v68
	v_mov_b32_e32 v68, v65
	v_mov_b32_e32 v65, v70
	v_mov_b32_e32 v70, v67
	s_waitcnt lgkmcnt(10)
	v_mov_b32_e32 v67, v76
	v_mov_b32_e32 v76, v73
	v_mov_b32_e32 v73, v78
	v_mov_b32_e32 v78, v75
	s_waitcnt lgkmcnt(8)
	v_mov_b32_e32 v75, v84
	v_mov_b32_e32 v84, v81
	v_mov_b32_e32 v81, v86
	v_mov_b32_e32 v86, v83
	s_waitcnt lgkmcnt(6)
	v_mov_b32_e32 v83, v92
	v_mov_b32_e32 v92, v89
	v_mov_b32_e32 v89, v94
	v_mov_b32_e32 v94, v91
	s_waitcnt lgkmcnt(4)
	v_mov_b32_e32 v91, v100
	v_mov_b32_e32 v100, v97
	v_mov_b32_e32 v97, v102
	v_mov_b32_e32 v102, v99
	s_waitcnt lgkmcnt(2)
	v_mov_b32_e32 v99, v108
	v_mov_b32_e32 v108, v105
	v_mov_b32_e32 v105, v110
	v_mov_b32_e32 v110, v107
	s_waitcnt lgkmcnt(0)
	v_mov_b32_e32 v107, v116
	v_mov_b32_e32 v116, v113
	v_mov_b32_e32 v128, v44
	v_mov_b32_e32 v44, v46
	v_mov_b32_e32 v46, v56
	v_mov_b32_e32 v56, v58
	v_mov_b32_e32 v58, v64
	v_mov_b32_e32 v64, v66
	v_mov_b32_e32 v66, v72
	v_mov_b32_e32 v72, v74
	v_mov_b32_e32 v74, v80
	v_mov_b32_e32 v80, v82
	v_mov_b32_e32 v82, v88
	v_mov_b32_e32 v88, v90
	v_mov_b32_e32 v90, v96
	v_mov_b32_e32 v96, v98
	v_mov_b32_e32 v98, v104
	v_mov_b32_e32 v104, v106
	v_mov_b32_e32 v106, v112
	v_mov_b32_e32 v112, v114
	v_mov_b32_e32 v113, v118
	v_add_u32_e32 v43, 4, v43
	v_mov_b32_e32 v118, v115
	v_cmp_ge_i32_e64 s[6:7], v43, v39
	v_add_u32_e32 v8, 16, v8
	v_lshl_add_u64 v[18:19], v[18:19], 0, s[12:13]
	s_or_b64 s[18:19], s[6:7], s[18:19]
	s_waitcnt vmcnt(4)
	v_mul_f32_e32 v114, v132, v51
	v_pk_mul_f32 v[60:61], v[134:135], v[60:61] op_sel_hi:[0,1]
	v_pk_mul_f32 v[68:69], v[134:135], v[68:69] op_sel_hi:[0,1]
	v_pk_mul_f32 v[76:77], v[134:135], v[76:77] op_sel_hi:[0,1]
	v_pk_mul_f32 v[84:85], v[134:135], v[84:85] op_sel_hi:[0,1]
	v_pk_mul_f32 v[92:93], v[134:135], v[92:93] op_sel_hi:[0,1]
	v_pk_mul_f32 v[100:101], v[134:135], v[100:101] op_sel_hi:[0,1]
	v_pk_mul_f32 v[108:109], v[134:135], v[108:109] op_sel_hi:[0,1]
	v_pk_mul_f32 v[116:117], v[134:135], v[116:117] op_sel_hi:[0,1]
	v_pk_mul_f32 v[2:3], v[134:135], v[2:3] op_sel_hi:[0,1]
	v_pk_fma_f32 v[46:47], v[138:139], v[46:47], v[60:61] op_sel_hi:[0,1,1]
	v_pk_fma_f32 v[58:59], v[138:139], v[58:59], v[68:69] op_sel_hi:[0,1,1]
	v_pk_fma_f32 v[60:61], v[138:139], v[66:67], v[76:77] op_sel_hi:[0,1,1]
	v_pk_fma_f32 v[66:67], v[138:139], v[74:75], v[84:85] op_sel_hi:[0,1,1]
	v_pk_fma_f32 v[68:69], v[138:139], v[82:83], v[92:93] op_sel_hi:[0,1,1]
	v_pk_fma_f32 v[74:75], v[138:139], v[90:91], v[100:101] op_sel_hi:[0,1,1]
	v_pk_fma_f32 v[76:77], v[138:139], v[98:99], v[108:109] op_sel_hi:[0,1,1]
	v_pk_fma_f32 v[82:83], v[138:139], v[106:107], v[116:117] op_sel_hi:[0,1,1]
	v_pk_fma_f32 v[2:3], v[138:139], v[128:129], v[2:3] op_sel_hi:[0,1,1]
	v_mov_b32_e32 v139, v134
	v_pk_fma_f32 v[46:47], v[136:137], v[56:57], v[46:47] op_sel_hi:[0,1,1]
	v_pk_fma_f32 v[56:57], v[136:137], v[64:65], v[58:59] op_sel_hi:[0,1,1]
	v_pk_fma_f32 v[58:59], v[136:137], v[72:73], v[60:61] op_sel_hi:[0,1,1]
	v_pk_fma_f32 v[60:61], v[136:137], v[80:81], v[66:67] op_sel_hi:[0,1,1]
	v_pk_fma_f32 v[64:65], v[136:137], v[88:89], v[68:69] op_sel_hi:[0,1,1]
	v_pk_fma_f32 v[66:67], v[136:137], v[96:97], v[74:75] op_sel_hi:[0,1,1]
	v_pk_fma_f32 v[68:69], v[136:137], v[104:105], v[76:77] op_sel_hi:[0,1,1]
	v_pk_fma_f32 v[72:73], v[136:137], v[112:113], v[82:83] op_sel_hi:[0,1,1]
	v_pk_fma_f32 v[2:3], v[136:137], v[44:45], v[2:3] op_sel_hi:[0,1,1]
	v_mov_b32_e32 v137, v132
	v_pk_mul_f32 v[44:45], v[138:139], v[52:53]
	v_mul_f32_e32 v48, v138, v48
	v_mul_f32_e32 v130, v134, v49
	v_pk_fma_f32 v[2:3], v[132:133], v[4:5], v[2:3] op_sel_hi:[0,1,1]
	v_pk_mul_f32 v[4:5], v[136:137], v[54:55]
	v_mov_b32_e32 v49, v44
	v_mov_b32_e32 v131, v45
	v_mul_f32_e32 v50, v136, v50
	v_pk_add_f32 v[36:37], v[36:37], v[2:3]
	v_pk_add_f32 v[2:3], v[48:49], v[130:131]
	v_mov_b32_e32 v51, v4
	v_mov_b32_e32 v115, v5
	v_pk_add_f32 v[2:3], v[50:51], v[2:3]
	v_pk_fma_f32 v[46:47], v[132:133], v[62:63], v[46:47] op_sel_hi:[0,1,1]
	v_pk_fma_f32 v[52:53], v[132:133], v[70:71], v[56:57] op_sel_hi:[0,1,1]
	v_pk_fma_f32 v[56:57], v[132:133], v[78:79], v[58:59] op_sel_hi:[0,1,1]
	v_pk_fma_f32 v[58:59], v[132:133], v[86:87], v[60:61] op_sel_hi:[0,1,1]
	v_pk_fma_f32 v[60:61], v[132:133], v[94:95], v[64:65] op_sel_hi:[0,1,1]
	v_pk_fma_f32 v[62:63], v[132:133], v[102:103], v[66:67] op_sel_hi:[0,1,1]
	v_pk_fma_f32 v[64:65], v[132:133], v[110:111], v[68:69] op_sel_hi:[0,1,1]
	v_pk_fma_f32 v[66:67], v[132:133], v[118:119], v[72:73] op_sel_hi:[0,1,1]
	v_pk_add_f32 v[2:3], v[114:115], v[2:3]
	v_pk_add_f32 v[20:21], v[20:21], v[46:47]
	v_pk_add_f32 v[22:23], v[22:23], v[52:53]
	v_pk_add_f32 v[24:25], v[24:25], v[56:57]
	v_pk_add_f32 v[26:27], v[26:27], v[58:59]
	v_pk_add_f32 v[28:29], v[28:29], v[60:61]
	v_pk_add_f32 v[30:31], v[30:31], v[62:63]
	v_pk_add_f32 v[32:33], v[32:33], v[64:65]
	v_pk_add_f32 v[34:35], v[34:35], v[66:67]
	v_pk_add_f32 v[16:17], v[16:17], v[2:3]
	s_andn2_b64 exec, exec, s[18:19]
	s_cbranch_execnz .LBB0_31
.Lada_kdone:
	s_waitcnt vmcnt(0)
	s_or_b64 exec, exec, s[18:19]
	ds_write2st64_b32 v42, v20, v21 offset1:1
	ds_write2st64_b32 v42, v22, v23 offset0:2 offset1:3
	ds_write2st64_b32 v42, v24, v25 offset0:4 offset1:5
	ds_write2st64_b32 v42, v26, v27 offset0:6 offset1:7
	ds_write2st64_b32 v42, v28, v29 offset0:8 offset1:9
	ds_write2st64_b32 v42, v30, v31 offset0:10 offset1:11
	ds_write2st64_b32 v42, v32, v33 offset0:12 offset1:13
	ds_write2st64_b32 v42, v34, v35 offset0:14 offset1:15
	ds_write2st64_b32 v42, v36, v37 offset0:16 offset1:17
	ds_write2st64_b32 v42, v16, v17 offset0:18 offset1:19
	s_waitcnt lgkmcnt(0)
	s_barrier
	s_and_saveexec_b64 s[18:19], vcc
	s_cbranch_execz .LBB0_24
	s_mul_i32 s6, s22, 0xc00
	s_add_i32 s6, s6, s16
	v_or_b32_e32 v2, s6, v1
	v_ashrrev_i32_e32 v3, 31, v2
	s_mul_hi_i32 s23, s22, 20
	s_mul_i32 s22, s22, 20
	v_lshl_add_u64 v[2:3], v[2:3], 2, s[14:15]
	v_lshl_add_u64 v[4:5], s[16:17], 2, v[10:11]
	s_mov_b64 s[16:17], 0
	v_mov_b32_e32 v8, v6
